# P2-producer-loop-store-latency-hidden
# baseline (speedup 1.0000x reference)
.LBB0_239:
.LBB0_240:
	s_cmp_lt_i32 s72, 3
	s_cselect_b64 s[4:5], -1, 0
	s_add_u32 s48, s70, 0x18c00000
	s_addc_u32 s49, s71, 0
	s_and_b64 s[22:23], s[4:5], s[0:1]
	s_andn2_b64 vcc, exec, s[22:23]
	s_cbranch_vccnz .LBB0_250
	s_cmp_lt_u32 s2, 64
	v_readfirstlane_b32 s3, v143
	s_cbranch_scc1 .LBB0_250
	v_writelane_b32 v240, s2, 0
	v_writelane_b32 v240, s74, 1
	s_mov_b32 s101, s3
	s_sub_u32 s98, s2, 64
	s_and_b32 s99, s98, 63
	s_lshl_b32 s99, s99, 5
	s_lshr_b32 s98, s98, 6
	s_or_b32 s2, s99, s98
	s_add_u32 s100, s99, 32
	s_mov_b32 s74, 3
	s_ashr_i32 s0, s2, 9
	s_ashr_i32 s1, s0, 31
	s_lshl_b32 s4, s2, 6
	v_lshrrev_b32_e32 v56, 7, v143
	s_lshl_b64 s[0:1], s[0:1], 11
	s_and_b32 s4, s4, 0x7c0
	s_or_b32 s0, s0, s4
	s_lshl_b32 s4, s2, 2
	s_waitcnt vmcnt(0)
	v_lshlrev_b32_e32 v22, 4, v56
	v_mov_b32_e32 v23, 0
	v_and_b32_e32 v64, 0x7f, v143
	s_and_b32 s4, s4, 0x780
	v_lshl_add_u64 v[2:3], s[0:1], 0, v[22:23]
	v_or_b32_e32 v58, s4, v64
	v_lshlrev_b64 v[2:3], 11, v[2:3]
	v_readlane_b32 s4, v242, 51
	v_or_b32_e32 v2, v2, v58
	v_readlane_b32 s5, v242, 52
	v_or_b32_e32 v24, 1, v22
	v_mov_b32_e32 v25, v23
	v_lshl_add_u64 v[4:5], v[2:3], 2, s[4:5]
	v_lshlrev_b64 v[2:3], 1, v[2:3]
	v_lshl_add_u64 v[6:7], s[38:39], 0, v[2:3]
	v_lshl_add_u64 v[8:9], s[48:49], 0, v[2:3]
	v_lshl_add_u64 v[2:3], s[0:1], 0, v[24:25]
	v_lshlrev_b64 v[2:3], 11, v[2:3]
	v_or_b32_e32 v2, v2, v58
	v_lshl_add_u64 v[10:11], v[2:3], 2, s[4:5]
	v_lshlrev_b64 v[2:3], 1, v[2:3]
	v_or_b32_e32 v26, 2, v22
	v_mov_b32_e32 v27, v23
	v_lshl_add_u64 v[12:13], s[38:39], 0, v[2:3]
	v_lshl_add_u64 v[14:15], s[48:49], 0, v[2:3]
	v_lshl_add_u64 v[2:3], s[0:1], 0, v[26:27]
	v_lshlrev_b64 v[2:3], 11, v[2:3]
	v_or_b32_e32 v2, v2, v58
	v_lshlrev_b64 v[18:19], 1, v[2:3]
	v_or_b32_e32 v28, 3, v22
	v_mov_b32_e32 v29, v23
	v_or_b32_e32 v30, 4, v22
	v_mov_b32_e32 v31, v23
	v_lshl_add_u64 v[16:17], v[2:3], 2, s[4:5]
	v_lshl_add_u64 v[20:21], s[38:39], 0, v[18:19]
	global_load_dword v2, v[4:5], off
	global_load_ushort v65, v[6:7], off
	global_load_ushort v66, v[8:9], off
	global_load_dword v1, v[10:11], off
	global_load_ushort v67, v[12:13], off
	global_load_ushort v68, v[14:15], off
	global_load_dword v4, v[16:17], off
	global_load_ushort v69, v[20:21], off
	v_lshl_add_u64 v[8:9], s[0:1], 0, v[28:29]
	v_lshl_add_u64 v[12:13], s[0:1], 0, v[30:31]
	v_lshlrev_b64 v[8:9], 11, v[8:9]
	v_lshlrev_b64 v[14:15], 11, v[12:13]
	v_or_b32_e32 v8, v8, v58
	v_or_b32_e32 v14, v14, v58
	v_lshl_add_u64 v[6:7], s[48:49], 0, v[18:19]
	v_lshl_add_u64 v[16:17], v[8:9], 2, s[4:5]
	v_lshlrev_b64 v[8:9], 1, v[8:9]
	v_lshl_add_u64 v[12:13], v[14:15], 2, s[4:5]
	v_lshlrev_b64 v[14:15], 1, v[14:15]
	v_or_b32_e32 v32, 5, v22
	v_mov_b32_e32 v33, v23
	v_or_b32_e32 v36, 7, v22
	v_mov_b32_e32 v37, v23
	v_lshl_add_u64 v[10:11], s[38:39], 0, v[8:9]
	v_lshl_add_u64 v[8:9], s[48:49], 0, v[8:9]
	v_lshl_add_u64 v[18:19], s[38:39], 0, v[14:15]
	v_lshl_add_u64 v[14:15], s[48:49], 0, v[14:15]
	global_load_ushort v77, v[6:7], off
	global_load_ushort v79, v[10:11], off
	global_load_ushort v81, v[8:9], off
	global_load_ushort v82, v[18:19], off
	global_load_ushort v84, v[14:15], off
	v_lshl_add_u64 v[6:7], s[0:1], 0, v[32:33]
	v_or_b32_e32 v34, 6, v22
	v_mov_b32_e32 v35, v23
	v_lshl_add_u64 v[38:39], s[0:1], 0, v[36:37]
	v_lshlrev_b64 v[6:7], 11, v[6:7]
	v_lshl_add_u64 v[10:11], s[0:1], 0, v[34:35]
	v_lshlrev_b64 v[38:39], 11, v[38:39]
	v_or_b32_e32 v6, v6, v58
	v_lshlrev_b64 v[10:11], 11, v[10:11]
	v_or_b32_e32 v38, v38, v58
	v_lshl_add_u64 v[18:19], v[6:7], 2, s[4:5]
	v_lshlrev_b64 v[6:7], 1, v[6:7]
	v_or_b32_e32 v10, v10, v58
	v_lshl_add_u64 v[40:41], v[38:39], 2, s[4:5]
	v_lshlrev_b64 v[38:39], 1, v[38:39]
	v_lshl_add_u64 v[8:9], s[38:39], 0, v[6:7]
	v_lshl_add_u64 v[6:7], s[48:49], 0, v[6:7]
	v_lshl_add_u64 v[14:15], v[10:11], 2, s[4:5]
	v_lshlrev_b64 v[10:11], 1, v[10:11]
	v_lshl_add_u64 v[42:43], s[38:39], 0, v[38:39]
	v_lshl_add_u64 v[38:39], s[48:49], 0, v[38:39]
	v_lshl_add_u64 v[20:21], s[38:39], 0, v[10:11]
	v_lshl_add_u64 v[10:11], s[48:49], 0, v[10:11]
	global_load_ushort v70, v[8:9], off
	global_load_ushort v71, v[6:7], off
	s_nop 0
	global_load_dword v6, v[14:15], off
	global_load_ushort v72, v[20:21], off
	global_load_ushort v73, v[10:11], off
	global_load_dword v7, v[40:41], off
	global_load_ushort v74, v[42:43], off
	global_load_ushort v75, v[38:39], off
	v_or_b32_e32 v38, 8, v22
	v_mov_b32_e32 v39, v23
	v_lshl_add_u64 v[8:9], s[0:1], 0, v[38:39]
	v_lshlrev_b64 v[8:9], 11, v[8:9]
	v_or_b32_e32 v8, v8, v58
	v_lshl_add_u64 v[10:11], v[8:9], 2, s[4:5]
	v_lshlrev_b64 v[8:9], 1, v[8:9]
	v_or_b32_e32 v40, 9, v22
	v_mov_b32_e32 v41, v23
	v_lshl_add_u64 v[14:15], s[38:39], 0, v[8:9]
	v_lshl_add_u64 v[20:21], s[48:49], 0, v[8:9]
	v_lshl_add_u64 v[8:9], s[0:1], 0, v[40:41]
	v_lshlrev_b64 v[8:9], 11, v[8:9]
	v_or_b32_e32 v8, v8, v58
	v_lshl_add_u64 v[44:45], v[8:9], 2, s[4:5]
	v_lshlrev_b64 v[8:9], 1, v[8:9]
	v_or_b32_e32 v42, 10, v22
	v_mov_b32_e32 v43, v23
	v_lshl_add_u64 v[46:47], s[38:39], 0, v[8:9]
	v_lshl_add_u64 v[48:49], s[48:49], 0, v[8:9]
	v_lshl_add_u64 v[8:9], s[0:1], 0, v[42:43]
	v_lshlrev_b64 v[8:9], 11, v[8:9]
	v_or_b32_e32 v8, v8, v58
	v_lshlrev_b64 v[52:53], 1, v[8:9]
	v_lshl_add_u64 v[50:51], v[8:9], 2, s[4:5]
	v_lshl_add_u64 v[54:55], s[38:39], 0, v[52:53]
	global_load_dword v8, v[10:11], off
	global_load_ushort v78, v[14:15], off
	global_load_ushort v80, v[20:21], off
	global_load_dword v9, v[44:45], off
	global_load_ushort v83, v[46:47], off
	global_load_ushort v85, v[48:49], off
	global_load_dword v10, v[50:51], off
	global_load_ushort v86, v[54:55], off
	v_or_b32_e32 v46, 12, v22
	v_mov_b32_e32 v47, v23
	v_or_b32_e32 v44, 11, v22
	v_mov_b32_e32 v45, v23
	v_lshl_add_u64 v[50:51], s[0:1], 0, v[46:47]
	v_lshl_add_u64 v[20:21], s[0:1], 0, v[44:45]
	v_lshlrev_b64 v[50:51], 11, v[50:51]
	v_lshlrev_b64 v[20:21], 11, v[20:21]
	v_or_b32_e32 v50, v50, v58
	v_or_b32_e32 v20, v20, v58
	v_lshl_add_u64 v[108:109], v[50:51], 2, s[4:5]
	v_lshlrev_b64 v[50:51], 1, v[50:51]
	v_lshl_add_u64 v[14:15], s[48:49], 0, v[52:53]
	v_lshl_add_u64 v[62:63], v[20:21], 2, s[4:5]
	v_lshlrev_b64 v[20:21], 1, v[20:21]
	v_lshl_add_u64 v[52:53], s[38:39], 0, v[50:51]
	v_lshl_add_u64 v[50:51], s[48:49], 0, v[50:51]
	v_lshl_add_u64 v[48:49], s[38:39], 0, v[20:21]
	v_lshl_add_u64 v[20:21], s[48:49], 0, v[20:21]
	global_load_ushort v97, v[14:15], off
	global_load_ushort v98, v[48:49], off
	global_load_ushort v99, v[20:21], off
	global_load_ushort v100, v[52:53], off
	global_load_ushort v101, v[50:51], off
	v_or_b32_e32 v50, 14, v22
	v_mov_b32_e32 v51, v23
	v_lshl_add_u64 v[52:53], s[0:1], 0, v[50:51]
	v_lshlrev_b64 v[52:53], 11, v[52:53]
	v_or_b32_e32 v52, v52, v58
	v_lshl_add_u64 v[104:105], v[52:53], 2, s[4:5]
	v_lshlrev_b64 v[52:53], 1, v[52:53]
	v_lshl_add_u64 v[106:107], s[38:39], 0, v[52:53]
	v_lshl_add_u64 v[110:111], s[48:49], 0, v[52:53]
	v_or_b32_e32 v52, 15, v22
	v_mov_b32_e32 v53, v23
	v_or_b32_e32 v48, 13, v22
	v_mov_b32_e32 v49, v23
	v_lshl_add_u64 v[54:55], s[0:1], 0, v[52:53]
	v_lshl_add_u64 v[14:15], s[0:1], 0, v[48:49]
	v_lshlrev_b64 v[54:55], 11, v[54:55]
	v_lshlrev_b64 v[14:15], 11, v[14:15]
	v_or_b32_e32 v54, v54, v58
	v_or_b32_e32 v14, v14, v58
	v_lshl_add_u64 v[112:113], v[54:55], 2, s[4:5]
	v_lshlrev_b64 v[54:55], 1, v[54:55]
	v_and_b32_e32 v5, 0x80, v143
	v_lshl_add_u64 v[20:21], v[14:15], 2, s[4:5]
	v_lshl_add_u64 v[114:115], s[38:39], 0, v[54:55]
	v_lshl_add_u64 v[116:117], s[48:49], 0, v[54:55]
	v_cmp_eq_u32_e64 s[0:1], 0, v5
	v_lshl_add_u32 v5, v64, 1, 0
	s_movk_i32 s4, 0x8e
	v_lshlrev_b32_e32 v54, 1, v143
	v_mad_u32_u24 v11, v64, s4, v5
	v_and_b32_e32 v54, 0x600, v54
	s_add_i32 s4, 0, 0x11800
	v_add_u32_e32 v90, s4, v54
	s_lshr_b32 s4, s3, 3
	v_and_b32_e32 v57, 15, v143
	s_and_b32 s6, s4, 0xffffff0
	s_lshr_b32 s7, s3, 2
	s_and_b32 s5, s4, 0xfffffe0
	v_or_b32_e32 v54, s6, v57
	s_movk_i32 s6, 0x110
	s_and_b32 s7, s7, 16
	v_mul_lo_u32 v54, v54, s6
	s_or_b32 s5, s5, s7
	v_add_u32_e32 v92, 0, v54
	v_or_b32_e32 v54, s5, v57
	v_mul_lo_u32 v54, v54, s6
	v_add_u32_e32 v94, 0, v54
	v_lshrrev_b32_e32 v54, 2, v143
	v_and_b32_e32 v54, 12, v54
	v_and_or_b32 v58, s4, 16, v54
	v_lshlrev_b32_e32 v89, 5, v56
	v_or_b32_e32 v57, s7, v57
	v_mul_u32_u24_e32 v87, 0x1100, v56
	v_or_b32_e32 v56, 2, v58
	v_lshlrev_b32_e32 v54, 3, v143
	v_cmp_gt_u32_e64 s[10:11], v56, v57
	v_or_b32_e32 v56, 3, v58
	v_and_b32_e32 v60, 0x1f8, v54
	v_lshlrev_b32_e32 v54, 4, v143
	v_cmp_gt_u32_e64 s[12:13], v56, v57
	v_lshrrev_b32_e32 v56, 4, v143
	s_lshl_b32 s3, s3, 3
	v_and_b32_e32 v55, 0xf0, v54
	v_mul_u32_u24_e32 v118, 0x110, v56
	v_lshrrev_b32_e32 v56, 3, v143
	s_and_b32 s34, s3, 0xfffffe00
	v_add_u32_e32 v95, 0, v55
	v_and_b32_e32 v55, 0x70, v54
	v_mul_u32_u24_e32 v119, 0x90, v56
	v_add_u32_e32 v56, 0x200, v143
	s_ashr_i32 s3, s2, 31
	v_add_u32_e32 v96, 0, v55
	v_mov_b32_e32 v55, v23
	v_cmp_gt_u32_e64 s[6:7], v58, v57
	v_cmp_lt_u32_e64 s[8:9], v58, v57
	v_lshrrev_b32_e32 v57, 4, v56
	v_lshrrev_b32_e32 v56, 3, v56
	s_lshl_b64 s[24:25], s[2:3], 10
	v_mul_u32_u24_e32 v120, 0x110, v57
	v_mul_u32_u24_e32 v121, 0x90, v56
	v_lshl_add_u64 v[56:57], s[24:25], 0, v[54:55]
	s_mov_b64 s[24:25], 0x17200000
	s_ashr_i32 s29, s74, 31
	s_mov_b32 s28, s74
	s_lshl_b64 s[26:27], s[2:3], 14
	v_lshl_add_u64 v[56:57], v[56:57], 0, s[24:25]
	s_lshl_b64 s[24:25], s[28:29], 10
	v_or_b32_e32 v58, s26, v54
	v_mov_b32_e32 v59, s27
	s_lshl_b64 s[26:27], s[28:29], 14
	s_lshl_b64 s[30:31], s[2:3], 12
	v_lshlrev_b64 v[14:15], 1, v[14:15]
	v_lshlrev_b32_e32 v76, 2, v143
	s_add_u32 s3, s34, s30
	v_lshl_add_u64 v[102:103], s[38:39], 0, v[14:15]
	v_lshl_add_u64 v[14:15], s[48:49], 0, v[14:15]
	v_xor_b32_e32 v3, 0x200, v76
	v_mul_u32_u24_e32 v88, 0x110, v24
	s_addc_u32 s30, 0, s31
	s_add_i32 s41, 0, 0x11c00
	v_add_u32_e32 v55, s41, v3
	v_add_u32_e32 v87, v5, v87
	v_add_u32_e32 v88, v5, v88
	v_add_u32_e32 v89, v11, v89
	global_load_ushort v102, v[102:103], off
	s_nop 0
	global_load_ushort v103, v[14:15], off
	s_nop 0
	global_load_dword v14, v[104:105], off
	s_nop 0
	global_load_ushort v104, v[106:107], off
	global_load_ushort v105, v[110:111], off
	s_nop 0
	global_load_ushort v106, v[114:115], off
	global_load_ushort v107, v[116:117], off
	global_load_dword v15, v[112:113], off
	global_load_dword v5, v[18:19], off
	s_nop 0
	global_load_dword v12, v[12:13], off
	s_nop 0
	global_load_dword v3, v[16:17], off
	global_load_dword v13, v[20:21], off
	s_nop 0
	global_load_dword v16, v[108:109], off
	global_load_dword v11, v[62:63], off
	v_or_b32_e32 v60, s3, v60
	v_mov_b32_e32 v61, s30
	s_mov_b64 s[30:31], 0x16a00000
	v_lshlrev_b32_e32 v91, 2, v64
	v_and_b32_e32 v93, 48, v143
	v_lshl_add_u64 v[60:61], v[60:61], 0, s[30:31]
	s_add_i32 s30, s2, s74
	v_cmp_gt_u32_e64 s[4:5], 64, v143
	s_lshl_b64 s[28:29], s[28:29], 12
	s_lshl_b32 s3, s30, 6
	s_lshl_b32 s36, s74, 6
	s_lshl_b32 s37, s30, 2
	s_lshl_b32 s40, s74, 2
	v_add_u32_e32 v90, v90, v91
	v_add_u32_e32 v91, v92, v93
	v_add_u32_e32 v92, v94, v93
	v_add_u32_e32 v93, v95, v118
	s_brev_b32 s42, 48
	v_add_u32_e32 v94, v96, v119
	s_mov_b32 s43, 0xe000000
	s_brev_b32 s44, 8
	v_add_u32_e32 v95, v95, v120
	v_add_u32_e32 v96, v96, v121
	s_mov_b32 s45, s2
	s_waitcnt vmcnt(0)
	s_branch .LBB0_244
.LBB0_243:
	s_or_b64 exec, exec, s[34:35]
	s_waitcnt lgkmcnt(0)
	s_barrier
	v_lshl_add_u64 v[56:57], v[56:57], 0, s[24:25]
	v_lshl_add_u64 v[58:59], v[58:59], 0, s[26:27]
	v_lshl_add_u64 v[60:61], v[60:61], 0, s[28:29]
	s_add_i32 s3, s3, s36
	s_andn2_b64 vcc, exec, s[30:31]
	s_add_i32 s37, s37, s40
	s_cbranch_vccz .Lp2_exit
	s_sub_u32 s98, s45, s74
	s_sub_u32 s98, s98, s74
	s_cmp_lt_i32 s98, s2
	s_cbranch_scc1 .Lp2_nopub
	s_cmp_gt_u32 s101, 63
	s_cbranch_scc1 .Lp2_nopub
	s_lshl_b32 s98, s98, 2
	s_add_u32 s98, s98, 0x8000
	v_mov_b32_e32 v238, s98
	v_mov_b32_e32 v239, 1
	global_store_dword v238, v239, s[70:71] sc1
.Lp2_nopub:
.LBB0_244:
	s_waitcnt vmcnt(54)
	v_add_f32_e32 v17, 0, v2
	s_waitcnt vmcnt(51)
	v_add_f32_e32 v17, v1, v17
	s_waitcnt vmcnt(48)
	v_add_f32_e32 v17, v4, v17
	s_waitcnt vmcnt(10)
	v_add_f32_e32 v17, v3, v17
	v_add_f32_e32 v17, v12, v17
	v_add_f32_e32 v17, v5, v17
	v_add_f32_e32 v17, v6, v17
	v_add_f32_e32 v17, v7, v17
	v_add_f32_e32 v17, v8, v17
	v_add_f32_e32 v17, v9, v17
	v_add_f32_e32 v17, v10, v17
	s_waitcnt vmcnt(7)
	v_add_f32_e32 v17, v11, v17
	v_add_f32_e32 v17, v16, v17
	v_add_f32_e32 v17, v13, v17
	v_add_f32_e32 v17, v14, v17
	v_add_f32_e32 v18, v15, v17
	v_add_u32_e32 v17, s41, v76
	ds_write_b32 v17, v18
	s_waitcnt lgkmcnt(0)
	s_barrier
	ds_read_b32 v20, v55
	v_mov_b32_e32 v21, v1
	s_waitcnt lgkmcnt(0)
	v_cndmask_b32_e64 v17, v20, 0, s[0:1]
	v_add_f32_e32 v19, v2, v17
	v_pk_add_f32 v[62:63], v[20:21], v[18:19]
	v_max_f32_e32 v17, 0xc2a00000, v19
	v_sub_f32_e32 v20, v62, v19
	v_mul_f32_e32 v18, 0x3fb8aa3b, v2
	v_mul_f32_e32 v19, 0x3fb8aa3b, v1
	v_sub_f32_e32 v21, v62, v63
	v_max_f32_e32 v112, 0xc2a00000, v63
	v_exp_f32_e32 v18, v18
	v_exp_f32_e32 v19, v19
	v_mul_f32_e32 v20, 0x3fb8aa3b, v20
	v_mul_f32_e32 v21, 0x3fb8aa3b, v21
	v_mul_f32_e32 v108, 0xbfb8aa3b, v17
	v_mul_f32_e32 v109, 0xbfb8aa3b, v112
	v_exp_f32_e32 v20, v20
	v_exp_f32_e32 v21, v21
	v_exp_f32_e32 v108, v108
	v_exp_f32_e32 v109, v109
	v_add_f32_e32 v63, v4, v63
	v_pk_add_f32 v[18:19], v[18:19], 1.0 op_sel_hi:[1,0] neg_lo:[1,0] neg_hi:[1,0]
	v_add_f32_e32 v110, v3, v63
	v_mul_f32_e32 v113, v18, v108
	v_mul_f32_e32 v114, v19, v109
	v_pk_mul_f32 v[18:19], v[18:19], v[20:21]
	v_mul_f32_e32 v20, 0x3fb8aa3b, v4
	v_mul_f32_e32 v21, 0x3fb8aa3b, v3
	v_sub_f32_e32 v108, v62, v63
	v_sub_f32_e32 v109, v62, v110
	v_max_f32_e32 v63, 0xc2a00000, v63
	v_max_f32_e32 v115, 0xc2a00000, v110
	v_exp_f32_e32 v20, v20
	v_exp_f32_e32 v21, v21
	v_mul_f32_e32 v108, 0x3fb8aa3b, v108
	v_mul_f32_e32 v109, 0x3fb8aa3b, v109
	v_mul_f32_e32 v111, 0xbfb8aa3b, v63
	v_mul_f32_e32 v116, 0xbfb8aa3b, v115
	v_exp_f32_e32 v108, v108
	v_exp_f32_e32 v109, v109
	v_exp_f32_e32 v111, v111
	v_exp_f32_e32 v116, v116
	v_pk_add_f32 v[20:21], v[20:21], 1.0 op_sel_hi:[1,0] neg_lo:[1,0] neg_hi:[1,0]
	v_add_f32_e32 v110, v12, v110
	v_mul_f32_e32 v117, v20, v111
	v_mul_f32_e32 v116, v21, v116
	v_pk_mul_f32 v[20:21], v[20:21], v[108:109]
	v_add_f32_e32 v111, v5, v110
	v_cvt_pk_bf16_f32 v18, v18, v19
	v_cvt_pk_bf16_f32 v19, v20, v21
	v_mul_f32_e32 v20, 0x3fb8aa3b, v12
	v_mul_f32_e32 v21, 0x3fb8aa3b, v5
	v_sub_f32_e32 v108, v62, v110
	v_sub_f32_e32 v109, v62, v111
	v_max_f32_e32 v118, 0xc2a00000, v110
	v_max_f32_e32 v119, 0xc2a00000, v111
	v_exp_f32_e32 v20, v20
	v_exp_f32_e32 v21, v21
	v_mul_f32_e32 v108, 0x3fb8aa3b, v108
	v_mul_f32_e32 v109, 0x3fb8aa3b, v109
	v_mul_f32_e32 v110, 0xbfb8aa3b, v118
	v_mul_f32_e32 v120, 0xbfb8aa3b, v119
	v_exp_f32_e32 v108, v108
	v_exp_f32_e32 v109, v109
	v_exp_f32_e32 v110, v110
	v_exp_f32_e32 v120, v120
	v_pk_add_f32 v[20:21], v[20:21], 1.0 op_sel_hi:[1,0] neg_lo:[1,0] neg_hi:[1,0]
	v_mul_f32_e32 v17, 0x3fb8aa3b, v17
	v_mul_f32_e32 v121, v20, v110
	v_mul_f32_e32 v120, v21, v120
	v_pk_mul_f32 v[20:21], v[20:21], v[108:109]
	v_exp_f32_e32 v17, v17
	v_cvt_pk_bf16_f32 v20, v20, v21
	v_mul_f32_e32 v21, 0x3fb8aa3b, v6
	v_exp_f32_e32 v108, v21
	v_mul_f32_e32 v21, 0x3fb8aa3b, v7
	v_exp_f32_e32 v109, v21
	v_add_f32_e32 v21, v6, v111
	v_add_f32_e32 v122, v7, v21
	v_sub_f32_e32 v110, v62, v21
	v_sub_f32_e32 v111, v62, v122
	v_max_f32_e32 v123, 0xc2a00000, v21
	v_max_f32_e32 v124, 0xc2a00000, v122
	v_mul_f32_e32 v110, 0x3fb8aa3b, v110
	v_mul_f32_e32 v111, 0x3fb8aa3b, v111
	v_mul_f32_e32 v21, 0xbfb8aa3b, v123
	v_mul_f32_e32 v125, 0xbfb8aa3b, v124
	v_exp_f32_e32 v110, v110
	v_exp_f32_e32 v111, v111
	v_exp_f32_e32 v21, v21
	v_exp_f32_e32 v125, v125
	v_pk_add_f32 v[108:109], v[108:109], 1.0 op_sel_hi:[1,0] neg_lo:[1,0] neg_hi:[1,0]
	s_nop 0
	v_mul_f32_e32 v126, v108, v21
	v_mul_f32_e32 v125, v109, v125
	v_pk_mul_f32 v[108:109], v[108:109], v[110:111]
	s_nop 0
	v_cvt_pk_bf16_f32 v21, v108, v109
	v_lshlrev_b32_e32 v108, 16, v65
	v_mul_f32_e32 v17, v17, v108
	v_cvt_pk_bf16_f32 v17, v17, s0
	ds_write_b16 v87, v17
	v_mul_f32_e32 v17, 0x3fb8aa3b, v112
	v_exp_f32_e32 v17, v17
	v_lshlrev_b32_e32 v108, 16, v67
	v_lshlrev_b32_e32 v109, 16, v78
	v_lshlrev_b32_e32 v112, 16, v83
	v_mul_f32_e32 v17, v17, v108
	v_cvt_pk_bf16_f32 v17, v17, s0
	ds_write_b16 v88, v17
	v_cvt_pk_bf16_f32 v17, v113, s0
	ds_write_b16 v87, v17 offset:17408
	v_cvt_pk_bf16_f32 v17, v114, s0
	ds_write_b16 v88, v17 offset:17408
	v_mul_f32_e32 v17, 0x3fb8aa3b, v63
	v_exp_f32_e32 v17, v17
	v_lshlrev_b32_e32 v63, 16, v69
	v_mul_f32_e32 v17, v17, v63
	v_cvt_pk_bf16_f32 v17, v17, s0
	ds_write_b16 v88, v17 offset:272
	v_mul_f32_e32 v17, 0x3fb8aa3b, v115
	v_exp_f32_e32 v17, v17
	v_lshlrev_b32_e32 v63, 16, v79
	v_lshlrev_b32_e32 v115, 16, v98
	v_mul_f32_e32 v17, v17, v63
	v_cvt_pk_bf16_f32 v17, v17, s0
	ds_write_b16 v88, v17 offset:544
	v_cvt_pk_bf16_f32 v17, v117, s0
	ds_write_b16 v88, v17 offset:17680
	v_cvt_pk_bf16_f32 v17, v116, s0
	ds_write_b16 v88, v17 offset:17952
	v_mul_f32_e32 v17, 0x3fb8aa3b, v118
	v_exp_f32_e32 v17, v17
	v_lshlrev_b32_e32 v63, 16, v82
	v_mul_f32_e32 v17, v17, v63
	v_cvt_pk_bf16_f32 v17, v17, s0
	ds_write_b16 v88, v17 offset:816
	v_mul_f32_e32 v17, 0x3fb8aa3b, v119
	v_exp_f32_e32 v17, v17
	v_lshlrev_b32_e32 v63, 16, v70
	v_mul_f32_e32 v17, v17, v63
	v_cvt_pk_bf16_f32 v17, v17, s0
	ds_write_b16 v88, v17 offset:1088
	v_cvt_pk_bf16_f32 v17, v121, s0
	ds_write_b16 v88, v17 offset:18224
	v_cvt_pk_bf16_f32 v17, v120, s0
	ds_write_b16 v88, v17 offset:18496
	v_mul_f32_e32 v17, 0x3fb8aa3b, v123
	v_exp_f32_e32 v17, v17
	v_lshlrev_b32_e32 v63, 16, v72
	v_lshlrev_b32_e32 v121, 16, v102
	v_mul_f32_e32 v17, v17, v63
	v_cvt_pk_bf16_f32 v17, v17, s0
	ds_write_b16 v88, v17 offset:1360
	v_mul_f32_e32 v17, 0x3fb8aa3b, v124
	v_exp_f32_e32 v17, v17
	v_lshlrev_b32_e32 v63, 16, v74
	v_mul_f32_e32 v17, v17, v63
	v_cvt_pk_bf16_f32 v17, v17, s0
	ds_write_b16 v88, v17 offset:1632
	v_cvt_pk_bf16_f32 v17, v126, s0
	ds_write_b16 v88, v17 offset:18768
	v_cvt_pk_bf16_f32 v17, v125, s0
	ds_write_b16 v88, v17 offset:19040
	v_add_f32_e32 v17, v8, v122
	v_max_f32_e32 v63, 0xc2a00000, v17
	v_mul_f32_e32 v108, 0x3fb8aa3b, v63
	v_exp_f32_e32 v108, v108
	v_mul_f32_e32 v63, 0xbfb8aa3b, v63
	v_exp_f32_e32 v63, v63
	v_add_f32_e32 v116, v9, v17
	v_mul_f32_e32 v108, v108, v109
	v_cvt_pk_bf16_f32 v108, v108, s0
	ds_write_b16 v88, v108 offset:1904
	v_mul_f32_e32 v108, 0x3fb8aa3b, v8
	v_mul_f32_e32 v109, 0x3fb8aa3b, v9
	v_exp_f32_e32 v108, v108
	v_exp_f32_e32 v109, v109
	v_max_f32_e32 v110, 0xc2a00000, v116
	v_mul_f32_e32 v111, 0x3fb8aa3b, v110
	v_exp_f32_e32 v111, v111
	v_pk_add_f32 v[108:109], v[108:109], 1.0 op_sel_hi:[1,0] neg_lo:[1,0] neg_hi:[1,0]
	v_lshlrev_b32_e32 v125, 16, v106
	v_mul_f32_e32 v63, v108, v63
	v_cvt_pk_bf16_f32 v63, v63, s0
	ds_write_b16 v88, v63 offset:19312
	v_mul_f32_e32 v63, 0xbfb8aa3b, v110
	v_exp_f32_e32 v63, v63
	v_mul_f32_e32 v111, v111, v112
	v_cvt_pk_bf16_f32 v111, v111, s0
	ds_write_b16 v88, v111 offset:2176
	v_mul_f32_e32 v63, v109, v63
	v_cvt_pk_bf16_f32 v63, v63, s0
	ds_write_b16 v88, v63 offset:19584
	v_add_f32_e32 v63, v10, v116
	v_max_f32_e32 v112, 0xc2a00000, v63
	v_mul_f32_e32 v110, 0x3fb8aa3b, v112
	v_exp_f32_e32 v110, v110
	v_lshlrev_b32_e32 v111, 16, v86
	v_mul_f32_e32 v112, 0xbfb8aa3b, v112
	v_exp_f32_e32 v112, v112
	v_mul_f32_e32 v110, v110, v111
	v_cvt_pk_bf16_f32 v110, v110, s0
	ds_write_b16 v88, v110 offset:2448
	v_mul_f32_e32 v110, 0x3fb8aa3b, v10
	v_mul_f32_e32 v111, 0x3fb8aa3b, v11
	v_exp_f32_e32 v110, v110
	v_exp_f32_e32 v111, v111
	v_add_f32_e32 v117, v11, v63
	v_max_f32_e32 v113, 0xc2a00000, v117
	v_mul_f32_e32 v114, 0x3fb8aa3b, v113
	v_pk_add_f32 v[110:111], v[110:111], 1.0 op_sel_hi:[1,0] neg_lo:[1,0] neg_hi:[1,0]
	v_exp_f32_e32 v114, v114
	v_mul_f32_e32 v112, v110, v112
	v_cvt_pk_bf16_f32 v112, v112, s0
	ds_write_b16 v88, v112 offset:19856
	v_mul_f32_e32 v112, 0xbfb8aa3b, v113
	v_exp_f32_e32 v112, v112
	v_mul_f32_e32 v114, v114, v115
	v_cvt_pk_bf16_f32 v114, v114, s0
	v_add_f32_e32 v118, v16, v117
	v_mul_f32_e32 v112, v111, v112
	ds_write_b16 v88, v114 offset:2720
	v_cvt_pk_bf16_f32 v112, v112, s0
	v_max_f32_e32 v114, 0xc2a00000, v118
	ds_write_b16 v88, v112 offset:20128
	v_mul_f32_e32 v112, 0x3fb8aa3b, v114
	v_exp_f32_e32 v112, v112
	v_lshlrev_b32_e32 v113, 16, v100
	v_mul_f32_e32 v114, 0xbfb8aa3b, v114
	v_exp_f32_e32 v114, v114
	v_mul_f32_e32 v112, v112, v113
	v_cvt_pk_bf16_f32 v112, v112, s0
	ds_write_b16 v88, v112 offset:2992
	v_mul_f32_e32 v112, 0x3fb8aa3b, v16
	v_mul_f32_e32 v113, 0x3fb8aa3b, v13
	v_exp_f32_e32 v112, v112
	v_exp_f32_e32 v113, v113
	v_add_f32_e32 v119, v13, v118
	v_max_f32_e32 v115, 0xc2a00000, v119
	v_mul_f32_e32 v120, 0x3fb8aa3b, v115
	v_pk_add_f32 v[112:113], v[112:113], 1.0 op_sel_hi:[1,0] neg_lo:[1,0] neg_hi:[1,0]
	v_exp_f32_e32 v120, v120
	v_mul_f32_e32 v114, v112, v114
	v_cvt_pk_bf16_f32 v114, v114, s0
	ds_write_b16 v88, v114 offset:20400
	v_mul_f32_e32 v114, 0xbfb8aa3b, v115
	v_exp_f32_e32 v114, v114
	v_mul_f32_e32 v120, v120, v121
	v_cvt_pk_bf16_f32 v120, v120, s0
	ds_write_b16 v88, v120 offset:3264
	v_mul_f32_e32 v114, v113, v114
	v_add_f32_e32 v120, v14, v119
	v_cvt_pk_bf16_f32 v114, v114, s0
	v_max_f32_e32 v121, 0xc2a00000, v120
	ds_write_b16 v88, v114 offset:20672
	v_mul_f32_e32 v114, 0x3fb8aa3b, v121
	v_exp_f32_e32 v114, v114
	v_lshlrev_b32_e32 v115, 16, v104
	v_mul_f32_e32 v121, 0xbfb8aa3b, v121
	v_exp_f32_e32 v121, v121
	v_mul_f32_e32 v114, v114, v115
	v_cvt_pk_bf16_f32 v114, v114, s0
	ds_write_b16 v88, v114 offset:3536
	v_mul_f32_e32 v114, 0x3fb8aa3b, v14
	v_mul_f32_e32 v115, 0x3fb8aa3b, v15
	v_exp_f32_e32 v114, v114
	v_exp_f32_e32 v115, v115
	v_add_f32_e32 v122, v15, v120
	v_max_f32_e32 v123, 0xc2a00000, v122
	v_mul_f32_e32 v124, 0x3fb8aa3b, v123
	v_pk_add_f32 v[114:115], v[114:115], 1.0 op_sel_hi:[1,0] neg_lo:[1,0] neg_hi:[1,0]
	v_exp_f32_e32 v124, v124
	v_mul_f32_e32 v121, v114, v121
	v_cvt_pk_bf16_f32 v121, v121, s0
	ds_write_b16 v88, v121 offset:20944
	v_mul_f32_e32 v121, 0xbfb8aa3b, v123
	v_exp_f32_e32 v121, v121
	v_mul_f32_e32 v124, v124, v125
	v_cvt_pk_bf16_f32 v124, v124, s0
	v_sub_f32_e32 v17, v62, v17
	v_mul_f32_e32 v121, v115, v121
	v_cvt_pk_bf16_f32 v121, v121, s0
	ds_write_b16 v88, v124 offset:3808
	ds_write_b16 v88, v121 offset:21216
	ds_write_b128 v89, v[18:21] offset:34816
	v_mul_f32_e32 v17, 0x3fb8aa3b, v17
	v_sub_f32_e32 v18, v62, v116
	v_mul_f32_e32 v19, 0x3fb8aa3b, v18
	v_exp_f32_e32 v18, v17
	v_sub_f32_e32 v17, v62, v63
	v_sub_f32_e32 v20, v62, v117
	v_mul_f32_e32 v17, 0x3fb8aa3b, v17
	v_mul_f32_e32 v21, 0x3fb8aa3b, v20
	v_exp_f32_e32 v19, v19
	v_exp_f32_e32 v20, v17
	v_exp_f32_e32 v21, v21
	v_sub_f32_e32 v17, v62, v118
	v_pk_mul_f32 v[18:19], v[108:109], v[18:19]
	v_mul_f32_e32 v17, 0x3fb8aa3b, v17
	v_pk_mul_f32 v[20:21], v[110:111], v[20:21]
	v_cvt_pk_bf16_f32 v18, v18, v19
	v_cvt_pk_bf16_f32 v19, v20, v21
	v_sub_f32_e32 v20, v62, v119
	v_mul_f32_e32 v21, 0x3fb8aa3b, v20
	v_exp_f32_e32 v20, v17
	v_exp_f32_e32 v21, v21
	v_sub_f32_e32 v17, v62, v120
	v_mul_f32_e32 v17, 0x3fb8aa3b, v17
	v_exp_f32_e32 v108, v17
	v_pk_mul_f32 v[20:21], v[112:113], v[20:21]
	s_nop 0
	v_cvt_pk_bf16_f32 v20, v20, v21
	v_sub_f32_e32 v21, v62, v122
	v_mul_f32_e32 v21, 0x3fb8aa3b, v21
	v_exp_f32_e32 v109, v21
	s_nop 0
	v_pk_mul_f32 v[108:109], v[114:115], v[108:109]
	s_nop 0
	v_cvt_pk_bf16_f32 v21, v108, v109
	ds_write_b128 v89, v[18:21] offset:34832
	v_lshl_or_b32 v18, v68, 16, v66
	v_lshl_or_b32 v19, v81, 16, v77
	v_lshl_or_b32 v20, v71, 16, v84
	v_lshl_or_b32 v21, v75, 16, v73
	ds_write_b128 v89, v[18:21] offset:53248
	v_lshl_or_b32 v18, v85, 16, v80
	v_lshl_or_b32 v19, v99, 16, v97
	v_lshl_or_b32 v20, v103, 16, v101
	v_lshl_or_b32 v21, v107, 16, v105
	ds_write_b128 v89, v[18:21] offset:53264
	s_and_saveexec_b64 s[30:31], s[0:1]
	s_cbranch_execz .LBB0_246
	v_mul_f32_e32 v17, 0x3fb8aa3b, v62
	v_exp_f32_e32 v17, v17
	ds_write_b32 v90, v17
.LBB0_246:
	s_or_b64 exec, exec, s[30:31]
	s_add_i32 s45, s45, s74
	s_waitcnt lgkmcnt(0)
	s_barrier
	s_cmp_ge_i32 s45, s100
	s_cselect_b64 s[30:31], -1, 0
	s_and_b64 vcc, exec, s[30:31]
	s_cbranch_vccnz .LBB0_248
	s_waitcnt vmcnt(0)
	s_ashr_i32 s34, s45, 9
	s_ashr_i32 s35, s34, 31
	s_lshl_b64 s[34:35], s[34:35], 11
	s_and_b32 s46, s3, 0x7c0
	s_or_b32 s34, s34, s46
	s_and_b32 s46, s37, 0x780
	v_lshl_add_u64 v[2:3], s[34:35], 0, v[22:23]
	v_or_b32_e32 v77, s46, v64
	v_lshlrev_b64 v[2:3], 11, v[2:3]
	v_readlane_b32 s46, v242, 51
	v_or_b32_e32 v2, v2, v77
	v_readlane_b32 s47, v242, 52
	v_lshl_add_u64 v[70:71], s[34:35], 0, v[36:37]
	v_lshlrev_b64 v[70:71], 11, v[70:71]
	v_lshl_add_u64 v[4:5], v[2:3], 2, s[46:47]
	v_lshlrev_b64 v[2:3], 1, v[2:3]
	v_lshl_add_u64 v[6:7], s[38:39], 0, v[2:3]
	v_lshl_add_u64 v[8:9], s[48:49], 0, v[2:3]
	v_lshl_add_u64 v[2:3], s[34:35], 0, v[24:25]
	v_lshlrev_b64 v[2:3], 11, v[2:3]
	v_or_b32_e32 v2, v2, v77
	v_lshl_add_u64 v[10:11], v[2:3], 2, s[46:47]
	v_lshlrev_b64 v[2:3], 1, v[2:3]
	v_lshl_add_u64 v[12:13], s[38:39], 0, v[2:3]
	v_lshl_add_u64 v[14:15], s[48:49], 0, v[2:3]
	v_lshl_add_u64 v[2:3], s[34:35], 0, v[26:27]
	v_lshlrev_b64 v[2:3], 11, v[2:3]
	v_or_b32_e32 v2, v2, v77
	v_lshlrev_b64 v[18:19], 1, v[2:3]
	v_lshl_add_u64 v[16:17], v[2:3], 2, s[46:47]
	v_lshl_add_u64 v[20:21], s[38:39], 0, v[18:19]
	global_load_dword v2, v[4:5], off
	global_load_ushort v65, v[6:7], off
	global_load_ushort v66, v[8:9], off
	global_load_dword v1, v[10:11], off
	global_load_ushort v67, v[12:13], off
	global_load_ushort v68, v[14:15], off
	global_load_dword v4, v[16:17], off
	global_load_ushort v69, v[20:21], off
	v_lshl_add_u64 v[6:7], s[34:35], 0, v[28:29]
	v_lshlrev_b64 v[6:7], 11, v[6:7]
	v_or_b32_e32 v6, v6, v77
	v_lshl_add_u64 v[16:17], v[6:7], 2, s[46:47]
	v_lshlrev_b64 v[6:7], 1, v[6:7]
	v_lshl_add_u64 v[12:13], s[48:49], 0, v[18:19]
	v_lshl_add_u64 v[18:19], s[38:39], 0, v[6:7]
	v_lshl_add_u64 v[20:21], s[48:49], 0, v[6:7]
	v_lshl_add_u64 v[6:7], s[34:35], 0, v[30:31]
	v_lshlrev_b64 v[6:7], 11, v[6:7]
	v_or_b32_e32 v6, v6, v77
	v_lshl_add_u64 v[62:63], v[6:7], 2, s[46:47]
	v_lshlrev_b64 v[6:7], 1, v[6:7]
	v_lshl_add_u64 v[108:109], s[38:39], 0, v[6:7]
	v_lshl_add_u64 v[110:111], s[48:49], 0, v[6:7]
	v_lshl_add_u64 v[6:7], s[34:35], 0, v[32:33]
	v_lshl_add_u64 v[10:11], s[34:35], 0, v[34:35]
	v_lshlrev_b64 v[6:7], 11, v[6:7]
	v_lshlrev_b64 v[10:11], 11, v[10:11]
	v_or_b32_e32 v6, v6, v77
	v_or_b32_e32 v10, v10, v77
	v_lshl_add_u64 v[112:113], v[6:7], 2, s[46:47]
	v_lshlrev_b64 v[6:7], 1, v[6:7]
	v_lshl_add_u64 v[14:15], v[10:11], 2, s[46:47]
	v_lshlrev_b64 v[10:11], 1, v[10:11]
	v_or_b32_e32 v70, v70, v77
	v_lshl_add_u64 v[8:9], s[38:39], 0, v[6:7]
	v_lshl_add_u64 v[6:7], s[48:49], 0, v[6:7]
	v_lshl_add_u64 v[72:73], s[38:39], 0, v[10:11]
	v_lshl_add_u64 v[74:75], v[70:71], 2, s[46:47]
	v_lshlrev_b64 v[70:71], 1, v[70:71]
	v_lshl_add_u64 v[10:11], s[48:49], 0, v[10:11]
	v_lshl_add_u64 v[78:79], s[38:39], 0, v[70:71]
	v_lshl_add_u64 v[80:81], s[48:49], 0, v[70:71]
	global_load_ushort v70, v[8:9], off
	global_load_ushort v71, v[6:7], off
	s_nop 0
	global_load_dword v6, v[14:15], off
	s_nop 0
	global_load_ushort v72, v[72:73], off
	s_nop 0
	global_load_ushort v73, v[10:11], off
	global_load_dword v7, v[74:75], off
	s_nop 0
	global_load_ushort v74, v[78:79], off
	global_load_ushort v75, v[80:81], off
	v_lshl_add_u64 v[8:9], s[34:35], 0, v[38:39]
	v_lshlrev_b64 v[8:9], 11, v[8:9]
	v_or_b32_e32 v8, v8, v77
	v_lshl_add_u64 v[10:11], v[8:9], 2, s[46:47]
	v_lshlrev_b64 v[8:9], 1, v[8:9]
	v_lshl_add_u64 v[14:15], s[38:39], 0, v[8:9]
	v_lshl_add_u64 v[80:81], s[48:49], 0, v[8:9]
	v_lshl_add_u64 v[8:9], s[34:35], 0, v[40:41]
	v_lshlrev_b64 v[8:9], 11, v[8:9]
	v_or_b32_e32 v8, v8, v77
	v_lshl_add_u64 v[82:83], v[8:9], 2, s[46:47]
	v_lshlrev_b64 v[8:9], 1, v[8:9]
	v_lshl_add_u64 v[84:85], s[38:39], 0, v[8:9]
	v_lshl_add_u64 v[98:99], s[48:49], 0, v[8:9]
	v_lshl_add_u64 v[8:9], s[34:35], 0, v[42:43]
	v_lshlrev_b64 v[8:9], 11, v[8:9]
	v_or_b32_e32 v8, v8, v77
	v_lshlrev_b64 v[102:103], 1, v[8:9]
	v_lshl_add_u64 v[100:101], v[8:9], 2, s[46:47]
	v_lshl_add_u64 v[104:105], s[38:39], 0, v[102:103]
	global_load_dword v8, v[10:11], off
	global_load_ushort v78, v[14:15], off
	s_nop 0
	global_load_ushort v80, v[80:81], off
	s_nop 0
	global_load_dword v9, v[82:83], off
	s_nop 0
	global_load_ushort v83, v[84:85], off
	s_nop 0
	global_load_ushort v85, v[98:99], off
	global_load_dword v10, v[100:101], off
	global_load_ushort v86, v[104:105], off
	v_lshl_add_u64 v[98:99], s[34:35], 0, v[44:45]
	v_lshlrev_b64 v[98:99], 11, v[98:99]
	v_or_b32_e32 v98, v98, v77
	v_lshl_add_u64 v[114:115], v[98:99], 2, s[46:47]
	v_lshlrev_b64 v[98:99], 1, v[98:99]
	v_lshl_add_u64 v[14:15], s[48:49], 0, v[102:103]
	v_lshl_add_u64 v[100:101], s[38:39], 0, v[98:99]
	v_lshl_add_u64 v[102:103], s[48:49], 0, v[98:99]
	v_lshl_add_u64 v[98:99], s[34:35], 0, v[46:47]
	v_lshlrev_b64 v[98:99], 11, v[98:99]
	v_or_b32_e32 v98, v98, v77
	v_lshl_add_u64 v[116:117], v[98:99], 2, s[46:47]
	v_lshlrev_b64 v[98:99], 1, v[98:99]
	v_lshl_add_u64 v[104:105], s[38:39], 0, v[98:99]
	v_lshl_add_u64 v[106:107], s[48:49], 0, v[98:99]
	global_load_ushort v97, v[14:15], off
	global_load_ushort v98, v[100:101], off
	global_load_ushort v99, v[102:103], off
	s_nop 0
	global_load_ushort v100, v[104:105], off
	global_load_ushort v101, v[106:107], off
	v_lshl_add_u64 v[104:105], s[34:35], 0, v[50:51]
	v_lshlrev_b64 v[104:105], 11, v[104:105]
	v_or_b32_e32 v104, v104, v77
	v_lshl_add_u64 v[14:15], s[34:35], 0, v[48:49]
	v_lshl_add_u64 v[106:107], v[104:105], 2, s[46:47]
	v_lshlrev_b64 v[104:105], 1, v[104:105]
	v_lshlrev_b64 v[14:15], 11, v[14:15]
	v_lshl_add_u64 v[120:121], s[38:39], 0, v[104:105]
	v_lshl_add_u64 v[122:123], s[48:49], 0, v[104:105]
	v_lshl_add_u64 v[104:105], s[34:35], 0, v[52:53]
	v_or_b32_e32 v14, v14, v77
	v_lshlrev_b64 v[104:105], 11, v[104:105]
	v_lshl_add_u64 v[118:119], v[14:15], 2, s[46:47]
	v_lshlrev_b64 v[14:15], 1, v[14:15]
	v_or_b32_e32 v104, v104, v77
	v_lshl_add_u64 v[102:103], s[38:39], 0, v[14:15]
	v_lshl_add_u64 v[14:15], s[48:49], 0, v[14:15]
	v_lshl_add_u64 v[124:125], v[104:105], 2, s[46:47]
	v_lshlrev_b64 v[104:105], 1, v[104:105]
	v_lshl_add_u64 v[126:127], s[38:39], 0, v[104:105]
	v_lshl_add_u64 v[128:129], s[48:49], 0, v[104:105]
	global_load_ushort v102, v[102:103], off
	s_nop 0
	global_load_ushort v103, v[14:15], off
	s_nop 0
	global_load_dword v14, v[106:107], off
	global_load_ushort v104, v[120:121], off
	global_load_ushort v105, v[122:123], off
	global_load_dword v15, v[124:125], off
	s_nop 0
	global_load_ushort v106, v[126:127], off
	global_load_ushort v107, v[128:129], off
	global_load_ushort v77, v[12:13], off
	global_load_ushort v79, v[18:19], off
	global_load_ushort v81, v[20:21], off
	global_load_ushort v82, v[108:109], off
	global_load_ushort v84, v[110:111], off
	global_load_dword v5, v[112:113], off
	global_load_dword v12, v[62:63], off
	global_load_dword v3, v[16:17], off
	global_load_dword v13, v[118:119], off
	s_nop 0
	global_load_dword v16, v[116:117], off
	global_load_dword v11, v[114:115], off

.Lp2_exit:
	s_waitcnt vmcnt(0)
	s_barrier
	s_cmp_gt_u32 s101, 63
	s_cbranch_scc1 .Lp2_nopub2
	v_mov_b32_e32 v239, 1
	s_sub_u32 s98, s45, s74
	s_sub_u32 s98, s98, s74
	s_cmp_lt_i32 s98, s2
	s_cbranch_scc1 .Lp2_nopub3
	s_lshl_b32 s98, s98, 2
	s_add_u32 s98, s98, 0x8000
	v_mov_b32_e32 v238, s98
	global_store_dword v238, v239, s[70:71] sc1
.Lp2_nopub3:
	s_sub_u32 s98, s45, s74
	s_lshl_b32 s98, s98, 2
	s_add_u32 s98, s98, 0x8000
	v_mov_b32_e32 v238, s98
	v_mov_b32_e32 v239, 1
	global_store_dword v238, v239, s[70:71] sc1
